# speedup vs baseline: 1.0131x; 1.0005x over previous
.LBB0_963:
	s_or_b64 exec, exec, s[34:35]
	v_add_u32_e32 v8, s63, v145
	v_add_u32_e32 v16, v146, v149
	ds_read_b128 v[8:11], v8
	ds_read_b128 v[12:15], v181
	ds_read_b128 v[16:19], v16
	v_add_u32_e32 v20, v147, v149
	ds_read_b128 v[20:23], v20
	s_waitcnt lgkmcnt(1)
	v_mfma_f32_16x16x32_bf16 v[0:3], v[8:11], v[16:19], v[0:3]
	ds_read_b32 v16, v151 offset:16640
	s_and_b64 s[34:35], s[48:49], exec
	s_cselect_b32 s48, 0x4000, s8
	s_waitcnt lgkmcnt(1)
	v_mfma_f32_16x16x32_bf16 v[0:3], v[12:15], v[20:23], v[0:3]
	v_add_u32_e32 v20, v147, v152
	s_cselect_b32 s51, 0, 0x17400
	ds_read_b128 v[20:23], v20
	s_cselect_b32 s50, 0x2000, s97
	s_add_i32 s62, s62, s77
	s_waitcnt lgkmcnt(1)
	s_nop 1
	v_pk_mul_f32 v[2:3], v[2:3], v[16:17] op_sel_hi:[1,0]
	v_pk_mul_f32 v[0:1], v[0:1], v[16:17] op_sel_hi:[1,0]
	v_add_u32_e32 v16, v146, v152
	ds_read_b128 v[16:19], v16
	s_waitcnt lgkmcnt(0)
	v_mfma_f32_16x16x32_bf16 v[4:7], v[8:11], v[16:19], v[4:7]
	ds_read_b32 v8, v153 offset:16640
	s_waitcnt lgkmcnt(0)
	s_barrier
	v_mfma_f32_16x16x32_bf16 v[4:7], v[12:15], v[20:23], v[4:7]
	s_nop 7
	v_pk_mul_f32 v[6:7], v[6:7], v[8:9] op_sel_hi:[1,0]
	v_pk_mul_f32 v[4:5], v[4:5], v[8:9] op_sel_hi:[1,0]
	v_cvt_pk_bf16_f32 v8, v0, s0
	ds_write_b16 v123, v8
	v_cvt_pk_bf16_f32 v8, v1, s0
	ds_write_b16 v123, v8 offset:144
	v_cvt_pk_bf16_f32 v8, v2, s0
	ds_write_b16 v123, v8 offset:288
	v_cvt_pk_bf16_f32 v8, v3, s0
	ds_write_b16 v123, v8 offset:432
	v_cvt_pk_bf16_f32 v8, v4, s0
	ds_write_b16 v124, v8
	v_cvt_pk_bf16_f32 v8, v5, s0
	ds_write_b16 v124, v8 offset:144
	v_cvt_pk_bf16_f32 v8, v6, s0
	ds_write_b16 v124, v8 offset:288
	v_cvt_pk_bf16_f32 v8, v7, s0
	ds_write_b16 v124, v8 offset:432
	ds_read2st64_b32 v[10:11], v182 offset0:74 offset1:75
	ds_read2st64_b32 v[8:9], v182 offset0:76 offset1:77
	s_waitcnt lgkmcnt(1)
	v_mov_b32_e32 v12, v11
	s_waitcnt lgkmcnt(0)
	v_lshl_add_u32 v243, v148, 2, s48
	ds_read_b32 v228, v243
	ds_read_b32 v229, v243 offset:4
	ds_read_b32 v230, v243 offset:8
	ds_read_b32 v231, v243 offset:12
	v_add_u32_e32 v243, s51, v183
	ds_read_b32 v232, v243
	v_add_u32_e32 v243, s51, v184
	ds_read_b32 v233, v243
	v_add_u32_e32 v243, s51, v185
	ds_read_b32 v234, v243
	v_add_u32_e32 v243, s51, v186
	ds_read_b32 v235, v243
	v_add_u32_e32 v243, s50, v183
	ds_read_b32 v236, v243
	v_add_u32_e32 v243, s50, v184
	ds_read_b32 v237, v243
	v_add_u32_e32 v243, s50, v185
	ds_read_b32 v238, v243
	v_add_u32_e32 v243, s50, v186
	ds_read_b32 v239, v243
	v_mov_b32_e32 v13, v9
	v_mov_b32_e32 v14, v10
	v_mov_b32_e32 v15, v8
	s_nop 1
	v_add_f32_dpp v14, v14, v14 quad_perm:[1,0,3,2] row_mask:0xf bank_mask:0xf
	v_add_f32_dpp v12, v12, v12 quad_perm:[1,0,3,2] row_mask:0xf bank_mask:0xf
	v_add_f32_dpp v15, v15, v15 quad_perm:[1,0,3,2] row_mask:0xf bank_mask:0xf
	v_add_f32_dpp v13, v13, v13 quad_perm:[1,0,3,2] row_mask:0xf bank_mask:0xf
	v_add_f32_dpp v14, v14, v14 quad_perm:[2,3,0,1] row_mask:0xf bank_mask:0xf
	v_add_f32_dpp v12, v12, v12 quad_perm:[2,3,0,1] row_mask:0xf bank_mask:0xf
	v_add_f32_dpp v15, v15, v15 quad_perm:[2,3,0,1] row_mask:0xf bank_mask:0xf
	v_add_f32_dpp v13, v13, v13 quad_perm:[2,3,0,1] row_mask:0xf bank_mask:0xf
	v_add_f32_dpp v14, v14, v14 row_half_mirror row_mask:0xf bank_mask:0xf
	v_add_f32_dpp v12, v12, v12 row_half_mirror row_mask:0xf bank_mask:0xf
	v_add_f32_dpp v15, v15, v15 row_half_mirror row_mask:0xf bank_mask:0xf
	v_add_f32_dpp v13, v13, v13 row_half_mirror row_mask:0xf bank_mask:0xf
	v_add_f32_dpp v14, v14, v14 row_mirror row_mask:0xf bank_mask:0xf
	v_add_f32_dpp v12, v12, v12 row_mirror row_mask:0xf bank_mask:0xf
	v_add_f32_dpp v15, v15, v15 row_mirror row_mask:0xf bank_mask:0xf
	v_add_f32_dpp v13, v13, v13 row_mirror row_mask:0xf bank_mask:0xf
	v_add_f32_dpp v14, v14, v14 row_bcast:15 row_mask:0xa bank_mask:0xf
	v_add_f32_dpp v12, v12, v12 row_bcast:15 row_mask:0xa bank_mask:0xf
	v_add_f32_dpp v15, v15, v15 row_bcast:15 row_mask:0xa bank_mask:0xf
	v_add_f32_dpp v13, v13, v13 row_bcast:15 row_mask:0xa bank_mask:0xf
	v_add_f32_dpp v14, v14, v14 row_bcast:31 row_mask:0xc bank_mask:0xf
	v_add_f32_dpp v12, v12, v12 row_bcast:31 row_mask:0xc bank_mask:0xf
	v_add_f32_dpp v15, v15, v15 row_bcast:31 row_mask:0xc bank_mask:0xf
	v_add_f32_dpp v13, v13, v13 row_bcast:31 row_mask:0xc bank_mask:0xf
	s_nop 1

	s_nop 0
	v_readlane_b32 s34, v14, 63
	v_readlane_b32 s35, v12, 63
	v_readlane_b32 s49, v15, 63
	v_readlane_b32 s52, v13, 63
	v_fma_f32 v12, s34, v111, v10
	v_fmac_f32_e32 v11, s35, v111
	v_fma_f32 v10, s49, v111, v8
	v_fmac_f32_e32 v9, s52, v111
	v_mul_f32_e32 v8, v12, v12
	v_mul_f32_e32 v13, v11, v11
	v_mul_f32_e32 v14, v10, v10
	v_mul_f32_e32 v15, v9, v9
	s_nop 1
	v_add_f32_dpp v8, v8, v8 quad_perm:[1,0,3,2] row_mask:0xf bank_mask:0xf
	v_add_f32_dpp v13, v13, v13 quad_perm:[1,0,3,2] row_mask:0xf bank_mask:0xf
	v_add_f32_dpp v14, v14, v14 quad_perm:[1,0,3,2] row_mask:0xf bank_mask:0xf
	v_add_f32_dpp v15, v15, v15 quad_perm:[1,0,3,2] row_mask:0xf bank_mask:0xf
	v_add_f32_dpp v8, v8, v8 quad_perm:[2,3,0,1] row_mask:0xf bank_mask:0xf
	v_add_f32_dpp v13, v13, v13 quad_perm:[2,3,0,1] row_mask:0xf bank_mask:0xf
	v_add_f32_dpp v14, v14, v14 quad_perm:[2,3,0,1] row_mask:0xf bank_mask:0xf
	v_add_f32_dpp v15, v15, v15 quad_perm:[2,3,0,1] row_mask:0xf bank_mask:0xf
	v_add_f32_dpp v8, v8, v8 row_half_mirror row_mask:0xf bank_mask:0xf
	v_add_f32_dpp v13, v13, v13 row_half_mirror row_mask:0xf bank_mask:0xf
	v_add_f32_dpp v14, v14, v14 row_half_mirror row_mask:0xf bank_mask:0xf
	v_add_f32_dpp v15, v15, v15 row_half_mirror row_mask:0xf bank_mask:0xf
	v_add_f32_dpp v8, v8, v8 row_mirror row_mask:0xf bank_mask:0xf
	v_add_f32_dpp v13, v13, v13 row_mirror row_mask:0xf bank_mask:0xf
	v_add_f32_dpp v14, v14, v14 row_mirror row_mask:0xf bank_mask:0xf
	v_add_f32_dpp v15, v15, v15 row_mirror row_mask:0xf bank_mask:0xf
	v_add_f32_dpp v8, v8, v8 row_bcast:15 row_mask:0xa bank_mask:0xf
	v_add_f32_dpp v13, v13, v13 row_bcast:15 row_mask:0xa bank_mask:0xf
	v_add_f32_dpp v14, v14, v14 row_bcast:15 row_mask:0xa bank_mask:0xf
	v_add_f32_dpp v15, v15, v15 row_bcast:15 row_mask:0xa bank_mask:0xf
	v_add_f32_dpp v8, v8, v8 row_bcast:31 row_mask:0xc bank_mask:0xf
	v_add_f32_dpp v13, v13, v13 row_bcast:31 row_mask:0xc bank_mask:0xf
	v_add_f32_dpp v14, v14, v14 row_bcast:31 row_mask:0xc bank_mask:0xf
	v_add_f32_dpp v15, v15, v15 row_bcast:31 row_mask:0xc bank_mask:0xf
	s_nop 1

	v_cmp_gt_i32_e64 s[34:35], s75, v148
	v_readlane_b32 s55, v8, 63
	v_readlane_b32 s54, v13, 63
	v_readlane_b32 s53, v14, 63
	v_readlane_b32 s52, v15, 63
	v_lshl_add_u32 v8, v148, 2, s48
	s_waitcnt lgkmcnt(0)
	s_and_saveexec_b64 s[48:49], s[34:35]
	s_cbranch_execz .LBB0_967
	v_fma_f32 v13, s55, v112, v27
	v_cmp_gt_f32_e64 s[34:35], s76, v13
	v_mul_f32_e32 v14, 0x4b800000, v13
	v_mov_b32_e32 v29, v228
	v_cndmask_b32_e64 v13, v13, v14, s[34:35]
	v_rsq_f32_e32 v13, v13
	s_nop 0
	v_mul_f32_e32 v14, 0x45800000, v13
	v_cndmask_b32_e64 v13, v13, v14, s[34:35]
	v_mul_f32_e32 v12, v12, v13
	v_mov_b32_e32 v13, v232
	v_pk_mul_f32 v[12:13], v[28:29], v[12:13]
	s_nop 0
	v_add_f32_e32 v12, v119, v12
	v_add_f32_e32 v12, v12, v13
	v_mov_b32_e32 v13, v236
	v_mul_f32_e32 v12, v13, v12
	v_cvt_pk_bf16_f32 v14, v12, s0
	v_add_u32_e32 v12, s62, v148
	v_ashrrev_i32_e32 v13, 31, v12
	v_lshlrev_b64 v[12:13], 13, v[12:13]
	v_lshl_add_u64 v[12:13], v[32:33], 0, v[12:13]
	global_store_short v[12:13], v14, off
	s_or_b64 exec, exec, s[48:49]
	v_cmp_gt_i32_e64 s[34:35], s75, v154
	s_and_saveexec_b64 s[48:49], s[34:35]
	s_cbranch_execnz .LBB0_968

.LBB0_966:
	v_fma_f32 v11, s53, v112, v27
	v_cmp_gt_f32_e64 s[34:35], s76, v11
	v_mul_f32_e32 v12, 0x4b800000, v11
	v_mov_b32_e32 v29, v230
	v_cndmask_b32_e64 v11, v11, v12, s[34:35]
	v_rsq_f32_e32 v11, v11
	s_nop 0
	v_mul_f32_e32 v12, 0x45800000, v11
	v_cndmask_b32_e64 v11, v11, v12, s[34:35]
	v_mul_f32_e32 v10, v10, v11
	v_mov_b32_e32 v11, v234
	v_pk_mul_f32 v[10:11], v[28:29], v[10:11]
	s_nop 0
	v_add_f32_e32 v10, v119, v10
	v_add_f32_e32 v10, v10, v11
	v_mov_b32_e32 v11, v238
	v_mul_f32_e32 v10, v11, v10
	v_cvt_pk_bf16_f32 v12, v10, s0
	v_add_u32_e32 v10, s62, v155
	v_ashrrev_i32_e32 v11, 31, v10
	v_lshlrev_b64 v[10:11], 13, v[10:11]
	v_lshl_add_u64 v[10:11], v[32:33], 0, v[10:11]
	global_store_short v[10:11], v12, off
	s_or_b64 exec, exec, s[48:49]
	v_cmp_gt_i32_e64 s[34:35], s75, v156
	s_and_saveexec_b64 s[48:49], s[34:35]
	s_cbranch_execz .LBB0_857
	s_branch .LBB0_970

.LBB0_968:
	v_fma_f32 v12, s54, v112, v27
	v_cmp_gt_f32_e64 s[34:35], s76, v12
	v_mul_f32_e32 v13, 0x4b800000, v12
	v_mov_b32_e32 v29, v229
	v_cndmask_b32_e64 v12, v12, v13, s[34:35]
	v_rsq_f32_e32 v12, v12
	s_nop 0
	v_mul_f32_e32 v13, 0x45800000, v12
	v_cndmask_b32_e64 v12, v12, v13, s[34:35]
	v_mul_f32_e32 v12, v11, v12
	v_mov_b32_e32 v13, v233
	v_pk_mul_f32 v[12:13], v[28:29], v[12:13]
	s_nop 0
	v_add_f32_e32 v11, v119, v12
	v_mov_b32_e32 v12, v237
	v_add_f32_e32 v11, v11, v13
	v_mul_f32_e32 v11, v12, v11
	v_add_u32_e32 v12, s62, v154
	v_ashrrev_i32_e32 v13, 31, v12
	v_lshlrev_b64 v[12:13], 13, v[12:13]
	v_cvt_pk_bf16_f32 v11, v11, s0
	v_lshl_add_u64 v[12:13], v[32:33], 0, v[12:13]
	global_store_short v[12:13], v11, off
	s_or_b64 exec, exec, s[48:49]
	v_cmp_gt_i32_e64 s[34:35], s75, v155
	s_and_saveexec_b64 s[48:49], s[34:35]
	s_cbranch_execnz .LBB0_966

.LBB0_970:
	v_fma_f32 v10, s52, v112, v27
	v_cmp_gt_f32_e64 s[34:35], s76, v10
	v_mul_f32_e32 v11, 0x4b800000, v10
	v_mov_b32_e32 v29, v231
	v_cndmask_b32_e64 v10, v10, v11, s[34:35]
	v_rsq_f32_e32 v10, v10
	v_mul_f32_e32 v11, 0x45800000, v10
	v_cndmask_b32_e64 v10, v10, v11, s[34:35]
	v_mov_b32_e32 v11, v235
	v_mul_f32_e32 v10, v9, v10
	v_pk_mul_f32 v[8:9], v[28:29], v[10:11]
	s_nop 0
	v_add_f32_e32 v8, v119, v8
	v_add_f32_e32 v8, v8, v9
	v_mov_b32_e32 v9, v239
	v_mul_f32_e32 v8, v9, v8
	v_cvt_pk_bf16_f32 v10, v8, s0
	v_add_u32_e32 v8, s62, v156
	v_ashrrev_i32_e32 v9, 31, v8
	v_lshlrev_b64 v[8:9], 13, v[8:9]
	v_lshl_add_u64 v[8:9], v[32:33], 0, v[8:9]
	global_store_short v[8:9], v10, off
	s_branch .LBB0_857

.LBB0_1099:
	s_andn2_b64 vcc, exec, s[20:21]
	s_cbranch_vccnz .LBB0_1346
	s_cmp_lg_u32 s43, 1
	s_mov_b64 s[20:21], -1
	s_cbranch_scc0 .LBB0_1198
	v_lshlrev_b32_e32 v128, 2, v157
	v_or_b32_e32 v137, v149, v145
	v_lshl_or_b32 v128, v153, 4, v128
	s_movk_i32 s20, 0x88
	v_mad_u64_u32 v[128:129], s[20:21], v137, s20, v[128:129]
	v_mul_f32_e32 v129, v117, v117
	v_fmac_f32_e32 v129, v116, v116
	v_fmac_f32_e32 v129, v118, v118
	v_fmac_f32_e32 v129, v119, v119
	v_fmac_f32_e32 v129, v112, v112
	v_fmac_f32_e32 v129, v113, v113
	v_fmac_f32_e32 v129, v114, v114
	v_fmac_f32_e32 v129, v115, v115
	ds_write_b32 v128, v129 offset:2176
	v_mul_f32_e32 v129, v109, v109
	v_fmac_f32_e32 v129, v108, v108
	v_fmac_f32_e32 v129, v110, v110
	v_fmac_f32_e32 v129, v111, v111
	v_fmac_f32_e32 v129, v104, v104
	v_fmac_f32_e32 v129, v105, v105
	v_fmac_f32_e32 v129, v106, v106
	v_fmac_f32_e32 v129, v107, v107
	v_mul_f32_e32 v130, v125, v125
	ds_write_b32 v128, v129 offset:4352
	v_mul_f32_e32 v129, v101, v101
	v_fmac_f32_e32 v130, v124, v124
	v_fmac_f32_e32 v129, v100, v100
	v_fmac_f32_e32 v130, v126, v126
	v_fmac_f32_e32 v129, v102, v102
	v_fmac_f32_e32 v130, v127, v127
	v_fmac_f32_e32 v129, v103, v103
	v_fmac_f32_e32 v130, v120, v120
	v_fmac_f32_e32 v129, v96, v96
	v_fmac_f32_e32 v130, v121, v121
	v_fmac_f32_e32 v129, v97, v97
	v_fmac_f32_e32 v130, v122, v122
	v_fmac_f32_e32 v129, v98, v98
	s_mov_b64 s[52:53], s[72:73]
	v_fmac_f32_e32 v130, v123, v123
	v_fmac_f32_e32 v129, v99, v99
	ds_write_b32 v128, v130
	ds_write_b32 v128, v129 offset:6528
	v_mul_f32_e32 v129, v93, v93
	v_fmac_f32_e32 v129, v92, v92
	v_fmac_f32_e32 v129, v94, v94
	v_fmac_f32_e32 v129, v95, v95
	v_fmac_f32_e32 v129, v88, v88
	v_fmac_f32_e32 v129, v89, v89
	v_fmac_f32_e32 v129, v90, v90
	v_fmac_f32_e32 v129, v91, v91
	ds_write_b32 v128, v129 offset:68
	v_mul_f32_e32 v129, v85, v85
	v_fmac_f32_e32 v129, v84, v84
	v_fmac_f32_e32 v129, v86, v86
	v_fmac_f32_e32 v129, v87, v87
	v_fmac_f32_e32 v129, v80, v80
	v_fmac_f32_e32 v129, v81, v81
	v_fmac_f32_e32 v129, v82, v82
	v_fmac_f32_e32 v129, v83, v83
	ds_write_b32 v128, v129 offset:2244
	v_mul_f32_e32 v129, v77, v77
	v_fmac_f32_e32 v129, v76, v76
	v_fmac_f32_e32 v129, v78, v78
	v_fmac_f32_e32 v129, v79, v79
	v_fmac_f32_e32 v129, v72, v72
	v_fmac_f32_e32 v129, v73, v73
	v_fmac_f32_e32 v129, v74, v74
	v_fmac_f32_e32 v129, v75, v75
	ds_write_b32 v128, v129 offset:4420
	v_mul_f32_e32 v129, v69, v69
	v_fmac_f32_e32 v129, v68, v68
	v_fmac_f32_e32 v129, v70, v70
	v_fmac_f32_e32 v129, v71, v71
	v_fmac_f32_e32 v129, v64, v64
	v_fmac_f32_e32 v129, v65, v65
	v_fmac_f32_e32 v129, v66, v66
	v_fmac_f32_e32 v129, v67, v67
	ds_write_b32 v128, v129 offset:6596
	v_mul_f32_e32 v129, v61, v61
	v_fmac_f32_e32 v129, v60, v60
	v_fmac_f32_e32 v129, v62, v62
	v_fmac_f32_e32 v129, v63, v63
	v_fmac_f32_e32 v129, v56, v56
	v_fmac_f32_e32 v129, v57, v57
	v_fmac_f32_e32 v129, v58, v58
	v_fmac_f32_e32 v129, v59, v59
	ds_write_b32 v128, v129 offset:17408
	v_mul_f32_e32 v129, v53, v53
	v_fmac_f32_e32 v129, v52, v52
	v_fmac_f32_e32 v129, v54, v54
	v_fmac_f32_e32 v129, v55, v55
	v_fmac_f32_e32 v129, v48, v48
	v_fmac_f32_e32 v129, v49, v49
	v_fmac_f32_e32 v129, v50, v50
	v_fmac_f32_e32 v129, v51, v51
	ds_write_b32 v128, v129 offset:19584
	v_mul_f32_e32 v129, v45, v45
	v_fmac_f32_e32 v129, v44, v44
	v_fmac_f32_e32 v129, v46, v46
	v_fmac_f32_e32 v129, v47, v47
	v_fmac_f32_e32 v129, v40, v40
	v_fmac_f32_e32 v129, v41, v41
	v_fmac_f32_e32 v129, v42, v42
	v_fmac_f32_e32 v129, v43, v43
	ds_write_b32 v128, v129 offset:21760
	v_mul_f32_e32 v129, v37, v37
	v_fmac_f32_e32 v129, v36, v36
	v_fmac_f32_e32 v129, v38, v38
	v_fmac_f32_e32 v129, v39, v39
	v_fmac_f32_e32 v129, v32, v32
	v_fmac_f32_e32 v129, v33, v33
	v_fmac_f32_e32 v129, v34, v34
	v_fmac_f32_e32 v129, v35, v35
	ds_write_b32 v128, v129 offset:23936
	v_mul_f32_e32 v129, v29, v29
	v_fmac_f32_e32 v129, v28, v28
	v_fmac_f32_e32 v129, v30, v30
	v_fmac_f32_e32 v129, v31, v31
	v_fmac_f32_e32 v129, v24, v24
	v_fmac_f32_e32 v129, v25, v25
	v_fmac_f32_e32 v129, v26, v26
	v_fmac_f32_e32 v129, v27, v27
	ds_write_b32 v128, v129 offset:17476
	v_mul_f32_e32 v129, v21, v21
	v_fmac_f32_e32 v129, v20, v20
	v_fmac_f32_e32 v129, v22, v22
	v_fmac_f32_e32 v129, v23, v23
	v_fmac_f32_e32 v129, v16, v16
	v_fmac_f32_e32 v129, v17, v17
	v_fmac_f32_e32 v129, v18, v18
	v_fmac_f32_e32 v129, v19, v19
	ds_write_b32 v128, v129 offset:19652
	v_mul_f32_e32 v129, v13, v13
	v_fmac_f32_e32 v129, v12, v12
	v_fmac_f32_e32 v129, v14, v14
	v_fmac_f32_e32 v129, v15, v15
	v_fmac_f32_e32 v129, v8, v8
	v_fmac_f32_e32 v129, v9, v9
	v_fmac_f32_e32 v129, v10, v10
	v_fmac_f32_e32 v129, v11, v11
	ds_write_b32 v128, v129 offset:21828
	v_mul_f32_e32 v129, v5, v5
	v_fmac_f32_e32 v129, v4, v4
	v_fmac_f32_e32 v129, v6, v6
	v_fmac_f32_e32 v129, v7, v7
	v_fmac_f32_e32 v129, v0, v0
	v_fmac_f32_e32 v129, v1, v1
	v_fmac_f32_e32 v129, v2, v2
	v_fmac_f32_e32 v129, v3, v3
	ds_write_b32 v128, v129 offset:24004
	s_movk_i32 s20, 0x44
	v_mul_lo_u32 v130, v197, s20
	s_waitcnt vmcnt(0) lgkmcnt(0)
	s_barrier
	ds_read2_b32 v[204:205], v130 offset1:1
	ds_read2_b32 v[206:207], v130 offset0:2 offset1:3
	ds_read2_b32 v[208:209], v130 offset0:4 offset1:5
	ds_read2_b32 v[210:211], v130 offset0:6 offset1:7
	ds_read2_b32 v[212:213], v130 offset0:8 offset1:9
	ds_read2_b32 v[214:215], v130 offset0:10 offset1:11
	ds_read2_b32 v[216:217], v130 offset0:12 offset1:13
	ds_read2_b32 v[218:219], v130 offset0:14 offset1:15
	s_add_i32 s20, s54, 0xfffff800
	s_ashr_i32 s20, s20, 5
	s_and_b32 s20, s20, 0xffffff80
	s_ashr_i32 s21, s20, 31
	s_waitcnt lgkmcnt(0)
	v_add_f32_e32 v131, 0, v204
	v_add_f32_e32 v132, 0, v205
	v_readlane_b32 s68, v252, 0
	s_lshl_b64 s[20:21], s[20:21], 2
	v_readlane_b32 s72, v252, 4
	v_readlane_b32 s69, v252, 1
	v_add_f32_e32 v133, 0, v206
	v_add_f32_e32 v134, 0, v207
	v_readlane_b32 s70, v252, 2
	v_readlane_b32 s71, v252, 3
	v_readlane_b32 s73, v252, 5
	s_add_u32 s20, s72, s20
	v_add_f32_e32 v131, v131, v208
	v_add_f32_e32 v132, v132, v209
	s_addc_u32 s21, s73, s21
	v_readlane_b32 s56, v252, 53
	v_readlane_b32 s70, v249, 3
	v_readlane_b32 s71, v249, 4
	v_add_f32_e32 v133, v133, v210
	v_add_f32_e32 v134, v134, v211
	v_readlane_b32 s57, v252, 54
	v_readlane_b32 s58, v252, 55
	v_readlane_b32 s59, v252, 56
	v_readlane_b32 s56, v249, 14
	v_add_f32_e32 v131, v131, v212
	v_add_f32_e32 v132, v132, v213
	v_mov_b32_e32 v141, v163
	v_readlane_b32 s58, v249, 16
	v_readlane_b32 s59, v249, 17
	v_add_u32_e32 v186, s50, v137
	v_add_f32_e32 v133, v133, v214
	v_add_f32_e32 v134, v134, v215
	v_lshl_add_u64 v[172:173], v[140:141], 1, s[58:59]
	v_readlane_b32 s74, v252, 6
	v_readlane_b32 s75, v252, 7
	v_readlane_b32 s60, v252, 57
	v_add_f32_e32 v131, v131, v216
	v_add_f32_e32 v132, v132, v217
	v_add_f32_e32 v131, v131, v132
	v_cndmask_b32_e64 v132, v196, 1.0, s[18:19]
	s_and_b64 s[18:19], s[18:19], exec
	s_mov_b64 s[18:19], s[70:71]
	v_add_f32_e32 v128, v133, v218
	v_add_f32_e32 v129, v134, v219
	v_add_f32_e32 v128, v128, v129
	v_lshlrev_b32_e32 v129, 6, v197
	v_add_f32_e32 v128, v131, v128
	v_sub_u32_e32 v129, v130, v129
	s_cselect_b32 s19, s19, s21
	s_cselect_b32 s18, s18, s20
	v_lshlrev_b32_e32 v133, 2, v139
	ds_write_b32 v129, v128 offset:34816
	s_waitcnt lgkmcnt(0)
	s_barrier
	global_load_dwordx4 v[128:131], v133, s[18:19]
	v_lshlrev_b32_e32 v139, 3, v137
	global_load_dwordx4 v[236:239], v133, s[18:19] offset:64
	ds_read_b32 v220, v139 offset:34816
	ds_read_b32 v221, v139 offset:34944
	ds_read_b32 v222, v139 offset:35072
	ds_read_b32 v223, v139 offset:35200
	ds_read_b32 v224, v139 offset:34820
	ds_read_b32 v225, v139 offset:34948
	ds_read_b32 v226, v139 offset:35076
	ds_read_b32 v227, v139 offset:35204
	ds_read_b32 v228, v139 offset:35840
	ds_read_b32 v229, v139 offset:35968
	ds_read_b32 v230, v139 offset:36096
	ds_read_b32 v231, v139 offset:36224
	ds_read_b32 v232, v139 offset:35844
	ds_read_b32 v233, v139 offset:35972
	ds_read_b32 v234, v139 offset:36100
	ds_read_b32 v235, v139 offset:36228
	v_readlane_b32 s61, v252, 58
	v_readlane_b32 s62, v252, 59
	v_readlane_b32 s63, v252, 60
	v_readlane_b32 s64, v252, 61
	v_readlane_b32 s65, v252, 62
	v_readlane_b32 s66, v252, 63
	v_readlane_b32 s67, v249, 0
	v_readlane_b32 s68, v249, 1
	v_readlane_b32 s69, v249, 2
	v_readlane_b32 s57, v249, 15
	s_waitcnt vmcnt(0)
	v_pk_mul_f32 v[178:179], v[132:133], v[130:131] op_sel_hi:[0,1]
	v_pk_mul_f32 v[180:181], v[132:133], v[128:129] op_sel_hi:[0,1]
	s_mov_b64 s[18:19], -1
	v_pk_mul_f32 v[176:177], v[132:133], v[236:237] op_sel_hi:[0,1]
	v_mov_b32_e32 v128, v220
	v_pk_mul_f32 v[174:175], v[132:133], v[238:239] op_sel_hi:[0,1]
	s_waitcnt lgkmcnt(0)
	v_mul_f32_e32 v128, v170, v128
	v_mul_f32_e32 v128, v170, v128
	v_fmamk_f32 v128, v128, 0x3c000000, v195
	v_cmp_gt_f32_e32 vcc, s80, v128
	v_mul_f32_e32 v129, 0x4b800000, v128
	s_nop 0
	v_cndmask_b32_e32 v128, v128, v129, vcc
	v_rsq_f32_e32 v128, v128
	s_nop 0
	v_mul_f32_e32 v129, 0x45800000, v128
	v_cndmask_b32_e32 v128, v128, v129, vcc
	v_mul_f32_e32 v132, v170, v128
	v_pk_mul_f32 v[128:129], v[124:125], v[132:133] op_sel_hi:[1,0]
	v_pk_mul_f32 v[130:131], v[126:127], v[132:133] op_sel_hi:[1,0]
	v_pk_mul_f32 v[182:183], v[120:121], v[132:133] op_sel_hi:[1,0]
	v_pk_mul_f32 v[132:133], v[122:123], v[132:133] op_sel_hi:[1,0]
	v_pk_mul_f32 v[130:131], v[178:179], v[130:131]
	v_pk_mul_f32 v[128:129], v[180:181], v[128:129]
	v_pk_mul_f32 v[134:135], v[174:175], v[132:133]
	v_pk_mul_f32 v[132:133], v[176:177], v[182:183]
	s_and_b64 vcc, exec, s[0:1]
	s_cbranch_vccz .LBB0_1103
	v_mad_i64_i32 v[184:185], s[18:19], v186, s36, v[172:173]
	v_add_co_u32_e32 v184, vcc, 0x15c2f000, v184
	v_cvt_pk_bf16_f32 v182, v128, v129
	v_cvt_pk_bf16_f32 v183, v130, v131
	v_addc_co_u32_e32 v185, vcc, 0, v185, vcc
	global_store_dwordx2 v[184:185], v[182:183], off
	v_cvt_pk_bf16_f32 v182, v132, v133
	v_cvt_pk_bf16_f32 v183, v134, v135
	global_store_dwordx2 v[184:185], v[182:183], off offset:32
	s_mov_b64 s[18:19], 0

.LBB0_1107:
	v_or_b32_e32 v128, 16, v137
	v_lshlrev_b32_e32 v143, 3, v128
	v_mov_b32_e32 v129, v221
	v_add_u32_e32 v188, s50, v128
	v_cndmask_b32_e64 v145, 0, 1, s[0:1]
	v_cmp_ne_u32_e64 s[18:19], 1, v145
	v_mul_f32_e32 v129, v166, v129
	v_mul_f32_e32 v129, v166, v129
	v_fmamk_f32 v129, v129, 0x3c000000, v195
	v_mul_f32_e32 v130, 0x4b800000, v129
	v_cmp_gt_f32_e32 vcc, s80, v129
	s_nop 1
	v_cndmask_b32_e32 v129, v129, v130, vcc
	v_rsq_f32_e32 v129, v129
	s_nop 0
	v_mul_f32_e32 v128, 0x45800000, v129
	v_cndmask_b32_e32 v128, v129, v128, vcc
	v_mul_f32_e32 v128, v166, v128
	v_pk_mul_f32 v[132:133], v[116:117], v[128:129] op_sel_hi:[1,0]
	v_pk_mul_f32 v[130:131], v[118:119], v[128:129] op_sel_hi:[1,0]
	v_pk_mul_f32 v[182:183], v[112:113], v[128:129] op_sel_hi:[1,0]
	v_pk_mul_f32 v[134:135], v[114:115], v[128:129] op_sel_hi:[1,0]
	v_pk_mul_f32 v[130:131], v[178:179], v[130:131]
	v_pk_mul_f32 v[128:129], v[180:181], v[132:133]
	v_pk_mul_f32 v[134:135], v[174:175], v[134:135]
	v_pk_mul_f32 v[132:133], v[176:177], v[182:183]
	s_andn2_b64 vcc, exec, s[0:1]
	s_mov_b64 s[0:1], -1
	s_cbranch_vccnz .LBB0_1109
	v_mad_i64_i32 v[190:191], s[0:1], v188, s36, v[172:173]
	v_add_co_u32_e32 v190, vcc, 0x15c2f000, v190
	v_cvt_pk_bf16_f32 v182, v128, v129
	v_cvt_pk_bf16_f32 v183, v130, v131
	v_addc_co_u32_e32 v191, vcc, 0, v191, vcc
	global_store_dwordx2 v[190:191], v[182:183], off
	v_cvt_pk_bf16_f32 v182, v132, v133
	v_cvt_pk_bf16_f32 v183, v134, v135
	s_mov_b64 s[0:1], 0
	global_store_dwordx2 v[190:191], v[182:183], off offset:32

.LBB0_1113:
	v_or_b32_e32 v128, 32, v137
	v_lshlrev_b32_e32 v145, 3, v128
	v_mov_b32_e32 v129, v222
	v_add_u32_e32 v190, s50, v128
	s_mov_b64 s[0:1], -1
	v_mul_f32_e32 v129, v160, v129
	v_mul_f32_e32 v129, v160, v129
	v_fmamk_f32 v129, v129, 0x3c000000, v195
	v_mul_f32_e32 v130, 0x4b800000, v129
	v_cmp_gt_f32_e32 vcc, s80, v129
	s_nop 1
	v_cndmask_b32_e32 v129, v129, v130, vcc
	v_rsq_f32_e32 v129, v129
	s_nop 0
	v_mul_f32_e32 v128, 0x45800000, v129
	v_cndmask_b32_e32 v128, v129, v128, vcc
	v_mul_f32_e32 v128, v160, v128
	v_pk_mul_f32 v[132:133], v[108:109], v[128:129] op_sel_hi:[1,0]
	v_pk_mul_f32 v[130:131], v[110:111], v[128:129] op_sel_hi:[1,0]
	v_pk_mul_f32 v[182:183], v[104:105], v[128:129] op_sel_hi:[1,0]
	v_pk_mul_f32 v[134:135], v[106:107], v[128:129] op_sel_hi:[1,0]
	v_pk_mul_f32 v[130:131], v[178:179], v[130:131]
	v_pk_mul_f32 v[128:129], v[180:181], v[132:133]
	v_pk_mul_f32 v[134:135], v[174:175], v[134:135]
	v_pk_mul_f32 v[132:133], v[176:177], v[182:183]
	s_and_b64 vcc, exec, s[18:19]
	s_cbranch_vccnz .LBB0_1115
	v_mad_i64_i32 v[192:193], s[0:1], v190, s36, v[172:173]
	v_add_co_u32_e32 v192, vcc, 0x15c2f000, v192
	v_cvt_pk_bf16_f32 v182, v128, v129
	v_cvt_pk_bf16_f32 v183, v130, v131
	v_addc_co_u32_e32 v193, vcc, 0, v193, vcc
	global_store_dwordx2 v[192:193], v[182:183], off
	v_cvt_pk_bf16_f32 v182, v132, v133
	v_cvt_pk_bf16_f32 v183, v134, v135
	s_mov_b64 s[0:1], 0
	global_store_dwordx2 v[192:193], v[182:183], off offset:32

.LBB0_1119:
	v_or_b32_e32 v128, 48, v137
	v_lshlrev_b32_e32 v147, 3, v128
	v_mov_b32_e32 v129, v223
	v_add_u32_e32 v192, s50, v128
	s_mov_b64 s[0:1], -1
	v_mul_f32_e32 v129, v156, v129
	v_mul_f32_e32 v129, v156, v129
	v_fmamk_f32 v129, v129, 0x3c000000, v195
	v_mul_f32_e32 v130, 0x4b800000, v129
	v_cmp_gt_f32_e32 vcc, s80, v129
	s_nop 1
	v_cndmask_b32_e32 v129, v129, v130, vcc
	v_rsq_f32_e32 v129, v129
	s_nop 0
	v_mul_f32_e32 v128, 0x45800000, v129
	v_cndmask_b32_e32 v128, v129, v128, vcc
	v_mul_f32_e32 v128, v156, v128
	v_pk_mul_f32 v[132:133], v[100:101], v[128:129] op_sel_hi:[1,0]
	v_pk_mul_f32 v[130:131], v[102:103], v[128:129] op_sel_hi:[1,0]
	v_pk_mul_f32 v[182:183], v[96:97], v[128:129] op_sel_hi:[1,0]
	v_pk_mul_f32 v[134:135], v[98:99], v[128:129] op_sel_hi:[1,0]
	v_pk_mul_f32 v[130:131], v[178:179], v[130:131]
	v_pk_mul_f32 v[128:129], v[180:181], v[132:133]
	v_pk_mul_f32 v[134:135], v[174:175], v[134:135]
	v_pk_mul_f32 v[132:133], v[176:177], v[182:183]
	s_and_b64 vcc, exec, s[18:19]
	s_cbranch_vccnz .LBB0_1121
	v_mad_i64_i32 v[198:199], s[0:1], v192, s36, v[172:173]
	v_add_co_u32_e32 v198, vcc, 0x15c2f000, v198
	v_cvt_pk_bf16_f32 v182, v128, v129
	v_cvt_pk_bf16_f32 v183, v130, v131
	v_addc_co_u32_e32 v199, vcc, 0, v199, vcc
	global_store_dwordx2 v[198:199], v[182:183], off
	v_cvt_pk_bf16_f32 v182, v132, v133
	v_cvt_pk_bf16_f32 v183, v134, v135
	s_mov_b64 s[0:1], 0
	global_store_dwordx2 v[198:199], v[182:183], off offset:32

.LBB0_1125:
	v_mov_b32_e32 v128, v224
	s_mov_b64 s[0:1], -1
	v_mul_f32_e32 v128, v170, v128
	v_mul_f32_e32 v128, v170, v128
	v_fmamk_f32 v128, v128, 0x3c000000, v195
	v_mul_f32_e32 v129, 0x4b800000, v128
	v_cmp_gt_f32_e32 vcc, s80, v128
	s_nop 1
	v_cndmask_b32_e32 v128, v128, v129, vcc
	v_rsq_f32_e32 v128, v128
	s_nop 0
	v_mul_f32_e32 v129, 0x45800000, v128
	v_cndmask_b32_e32 v128, v128, v129, vcc
	v_mul_f32_e32 v128, v170, v128
	v_pk_mul_f32 v[132:133], v[92:93], v[128:129] op_sel_hi:[1,0]
	v_pk_mul_f32 v[130:131], v[94:95], v[128:129] op_sel_hi:[1,0]
	v_pk_mul_f32 v[182:183], v[88:89], v[128:129] op_sel_hi:[1,0]
	v_pk_mul_f32 v[134:135], v[90:91], v[128:129] op_sel_hi:[1,0]
	v_pk_mul_f32 v[130:131], v[178:179], v[130:131]
	v_pk_mul_f32 v[128:129], v[180:181], v[132:133]
	v_pk_mul_f32 v[134:135], v[174:175], v[134:135]
	v_pk_mul_f32 v[132:133], v[176:177], v[182:183]
	s_and_b64 vcc, exec, s[18:19]
	s_cbranch_vccnz .LBB0_1127
	v_mad_i64_i32 v[198:199], s[0:1], v186, s36, v[172:173]
	v_add_co_u32_e32 v198, vcc, 0x15c2f000, v198
	v_cvt_pk_bf16_f32 v182, v128, v129
	v_cvt_pk_bf16_f32 v183, v130, v131
	v_addc_co_u32_e32 v199, vcc, 0, v199, vcc
	global_store_dwordx2 v[198:199], v[182:183], off offset:256
	v_cvt_pk_bf16_f32 v182, v132, v133
	v_cvt_pk_bf16_f32 v183, v134, v135
	s_mov_b64 s[0:1], 0
	global_store_dwordx2 v[198:199], v[182:183], off offset:288

.LBB0_1131:
	v_mov_b32_e32 v128, v225
	s_mov_b64 s[0:1], -1
	v_mul_f32_e32 v128, v166, v128
	v_mul_f32_e32 v128, v166, v128
	v_fmamk_f32 v128, v128, 0x3c000000, v195
	v_mul_f32_e32 v129, 0x4b800000, v128
	v_cmp_gt_f32_e32 vcc, s80, v128
	s_nop 1
	v_cndmask_b32_e32 v128, v128, v129, vcc
	v_rsq_f32_e32 v128, v128
	s_nop 0
	v_mul_f32_e32 v129, 0x45800000, v128
	v_cndmask_b32_e32 v128, v128, v129, vcc
	v_mul_f32_e32 v128, v166, v128
	v_pk_mul_f32 v[132:133], v[84:85], v[128:129] op_sel_hi:[1,0]
	v_pk_mul_f32 v[130:131], v[86:87], v[128:129] op_sel_hi:[1,0]
	v_pk_mul_f32 v[186:187], v[80:81], v[128:129] op_sel_hi:[1,0]
	v_pk_mul_f32 v[134:135], v[82:83], v[128:129] op_sel_hi:[1,0]
	v_pk_mul_f32 v[130:131], v[178:179], v[130:131]
	v_pk_mul_f32 v[128:129], v[180:181], v[132:133]
	v_pk_mul_f32 v[134:135], v[174:175], v[134:135]
	v_pk_mul_f32 v[132:133], v[176:177], v[186:187]
	s_and_b64 vcc, exec, s[18:19]
	s_cbranch_vccnz .LBB0_1133
	v_mad_i64_i32 v[198:199], s[0:1], v188, s36, v[172:173]
	v_add_co_u32_e32 v198, vcc, 0x15c2f000, v198
	v_cvt_pk_bf16_f32 v186, v128, v129
	v_cvt_pk_bf16_f32 v187, v130, v131
	v_addc_co_u32_e32 v199, vcc, 0, v199, vcc
	global_store_dwordx2 v[198:199], v[186:187], off offset:256
	v_cvt_pk_bf16_f32 v186, v132, v133
	v_cvt_pk_bf16_f32 v187, v134, v135
	s_mov_b64 s[0:1], 0
	global_store_dwordx2 v[198:199], v[186:187], off offset:288

.LBB0_1137:
	v_mov_b32_e32 v128, v226
	s_mov_b64 s[0:1], -1
	v_mul_f32_e32 v128, v160, v128
	v_mul_f32_e32 v128, v160, v128
	v_fmamk_f32 v128, v128, 0x3c000000, v195
	v_mul_f32_e32 v129, 0x4b800000, v128
	v_cmp_gt_f32_e32 vcc, s80, v128
	s_nop 1
	v_cndmask_b32_e32 v128, v128, v129, vcc
	v_rsq_f32_e32 v128, v128
	s_nop 0
	v_mul_f32_e32 v129, 0x45800000, v128
	v_cndmask_b32_e32 v128, v128, v129, vcc
	v_mul_f32_e32 v128, v160, v128
	v_pk_mul_f32 v[132:133], v[76:77], v[128:129] op_sel_hi:[1,0]
	v_pk_mul_f32 v[130:131], v[78:79], v[128:129] op_sel_hi:[1,0]
	v_pk_mul_f32 v[186:187], v[72:73], v[128:129] op_sel_hi:[1,0]
	v_pk_mul_f32 v[134:135], v[74:75], v[128:129] op_sel_hi:[1,0]
	v_pk_mul_f32 v[130:131], v[178:179], v[130:131]
	v_pk_mul_f32 v[128:129], v[180:181], v[132:133]
	v_pk_mul_f32 v[134:135], v[174:175], v[134:135]
	v_pk_mul_f32 v[132:133], v[176:177], v[186:187]
	s_and_b64 vcc, exec, s[18:19]
	s_cbranch_vccnz .LBB0_1139
	v_mad_i64_i32 v[188:189], s[0:1], v190, s36, v[172:173]
	v_add_co_u32_e32 v188, vcc, 0x15c2f000, v188
	v_cvt_pk_bf16_f32 v186, v128, v129
	v_cvt_pk_bf16_f32 v187, v130, v131
	v_addc_co_u32_e32 v189, vcc, 0, v189, vcc
	global_store_dwordx2 v[188:189], v[186:187], off offset:256
	v_cvt_pk_bf16_f32 v186, v132, v133
	v_cvt_pk_bf16_f32 v187, v134, v135
	s_mov_b64 s[0:1], 0
	global_store_dwordx2 v[188:189], v[186:187], off offset:288

.LBB0_1143:
	v_mov_b32_e32 v128, v227
	s_mov_b64 s[0:1], -1
	v_mul_f32_e32 v128, v156, v128
	v_mul_f32_e32 v128, v156, v128
	v_fmamk_f32 v128, v128, 0x3c000000, v195
	v_mul_f32_e32 v129, 0x4b800000, v128
	v_cmp_gt_f32_e32 vcc, s80, v128
	s_nop 1
	v_cndmask_b32_e32 v128, v128, v129, vcc
	v_rsq_f32_e32 v128, v128
	s_nop 0
	v_mul_f32_e32 v129, 0x45800000, v128
	v_cndmask_b32_e32 v128, v128, v129, vcc
	v_mul_f32_e32 v128, v156, v128
	v_pk_mul_f32 v[132:133], v[68:69], v[128:129] op_sel_hi:[1,0]
	v_pk_mul_f32 v[130:131], v[70:71], v[128:129] op_sel_hi:[1,0]
	v_pk_mul_f32 v[186:187], v[64:65], v[128:129] op_sel_hi:[1,0]
	v_pk_mul_f32 v[134:135], v[66:67], v[128:129] op_sel_hi:[1,0]
	v_pk_mul_f32 v[130:131], v[178:179], v[130:131]
	v_pk_mul_f32 v[128:129], v[180:181], v[132:133]
	v_pk_mul_f32 v[134:135], v[174:175], v[134:135]
	v_pk_mul_f32 v[132:133], v[176:177], v[186:187]
	s_and_b64 vcc, exec, s[18:19]
	s_cbranch_vccnz .LBB0_1145
	v_mad_i64_i32 v[188:189], s[0:1], v192, s36, v[172:173]
	v_add_co_u32_e32 v188, vcc, 0x15c2f000, v188
	v_cvt_pk_bf16_f32 v186, v128, v129
	v_cvt_pk_bf16_f32 v187, v130, v131
	v_addc_co_u32_e32 v189, vcc, 0, v189, vcc
	global_store_dwordx2 v[188:189], v[186:187], off offset:256
	v_cvt_pk_bf16_f32 v186, v132, v133
	v_cvt_pk_bf16_f32 v187, v134, v135
	s_mov_b64 s[0:1], 0
	global_store_dwordx2 v[188:189], v[186:187], off offset:288

.LBB0_1149:
	v_add_u32_e32 v128, 0x80, v137
	v_lshlrev_b32_e32 v139, 3, v128
	v_mov_b32_e32 v129, v228
	v_add_u32_e32 v188, s50, v128
	s_mov_b64 s[0:1], -1
	v_mul_f32_e32 v129, v152, v129
	v_mul_f32_e32 v129, v152, v129
	v_fmamk_f32 v129, v129, 0x3c000000, v195
	v_mul_f32_e32 v130, 0x4b800000, v129
	v_cmp_gt_f32_e32 vcc, s80, v129
	s_nop 1
	v_cndmask_b32_e32 v129, v129, v130, vcc
	v_rsq_f32_e32 v129, v129
	s_nop 0
	v_mul_f32_e32 v128, 0x45800000, v129
	v_cndmask_b32_e32 v128, v129, v128, vcc
	v_mul_f32_e32 v128, v152, v128
	v_pk_mul_f32 v[132:133], v[60:61], v[128:129] op_sel_hi:[1,0]
	v_pk_mul_f32 v[130:131], v[62:63], v[128:129] op_sel_hi:[1,0]
	v_pk_mul_f32 v[186:187], v[56:57], v[128:129] op_sel_hi:[1,0]
	v_pk_mul_f32 v[134:135], v[58:59], v[128:129] op_sel_hi:[1,0]
	v_pk_mul_f32 v[130:131], v[178:179], v[130:131]
	v_pk_mul_f32 v[128:129], v[180:181], v[132:133]
	v_pk_mul_f32 v[134:135], v[174:175], v[134:135]
	v_pk_mul_f32 v[132:133], v[176:177], v[186:187]
	s_and_b64 vcc, exec, s[18:19]
	s_cbranch_vccnz .LBB0_1151
	v_mad_i64_i32 v[190:191], s[0:1], v188, s36, v[172:173]
	v_add_co_u32_e32 v190, vcc, 0x15c2f000, v190
	v_cvt_pk_bf16_f32 v186, v128, v129
	v_cvt_pk_bf16_f32 v187, v130, v131
	v_addc_co_u32_e32 v191, vcc, 0, v191, vcc
	global_store_dwordx2 v[190:191], v[186:187], off
	v_cvt_pk_bf16_f32 v186, v132, v133
	v_cvt_pk_bf16_f32 v187, v134, v135
	s_mov_b64 s[0:1], 0
	global_store_dwordx2 v[190:191], v[186:187], off offset:32

.LBB0_1155:
	v_add_u32_e32 v128, 0x90, v137
	v_lshlrev_b32_e32 v143, 3, v128
	v_mov_b32_e32 v129, v229
	v_add_u32_e32 v190, s50, v128
	s_mov_b64 s[0:1], -1
	v_mul_f32_e32 v129, v148, v129
	v_mul_f32_e32 v129, v148, v129
	v_fmamk_f32 v129, v129, 0x3c000000, v195
	v_mul_f32_e32 v130, 0x4b800000, v129
	v_cmp_gt_f32_e32 vcc, s80, v129
	s_nop 1
	v_cndmask_b32_e32 v129, v129, v130, vcc
	v_rsq_f32_e32 v129, v129
	s_nop 0
	v_mul_f32_e32 v128, 0x45800000, v129
	v_cndmask_b32_e32 v128, v129, v128, vcc
	v_mul_f32_e32 v128, v148, v128
	v_pk_mul_f32 v[132:133], v[52:53], v[128:129] op_sel_hi:[1,0]
	v_pk_mul_f32 v[130:131], v[54:55], v[128:129] op_sel_hi:[1,0]
	v_pk_mul_f32 v[186:187], v[48:49], v[128:129] op_sel_hi:[1,0]
	v_pk_mul_f32 v[134:135], v[50:51], v[128:129] op_sel_hi:[1,0]
	v_pk_mul_f32 v[130:131], v[178:179], v[130:131]
	v_pk_mul_f32 v[128:129], v[180:181], v[132:133]
	v_pk_mul_f32 v[134:135], v[174:175], v[134:135]
	v_pk_mul_f32 v[132:133], v[176:177], v[186:187]
	s_and_b64 vcc, exec, s[18:19]
	s_cbranch_vccnz .LBB0_1157
	v_mad_i64_i32 v[192:193], s[0:1], v190, s36, v[172:173]
	v_add_co_u32_e32 v192, vcc, 0x15c2f000, v192
	v_cvt_pk_bf16_f32 v186, v128, v129
	v_cvt_pk_bf16_f32 v187, v130, v131
	v_addc_co_u32_e32 v193, vcc, 0, v193, vcc
	global_store_dwordx2 v[192:193], v[186:187], off
	v_cvt_pk_bf16_f32 v186, v132, v133
	v_cvt_pk_bf16_f32 v187, v134, v135
	s_mov_b64 s[0:1], 0
	global_store_dwordx2 v[192:193], v[186:187], off offset:32

.LBB0_1161:
	v_add_u32_e32 v128, 0xa0, v137
	v_lshlrev_b32_e32 v145, 3, v128
	v_mov_b32_e32 v129, v230
	v_add_u32_e32 v192, s50, v128
	s_mov_b64 s[0:1], -1
	v_mul_f32_e32 v129, v144, v129
	v_mul_f32_e32 v129, v144, v129
	v_fmamk_f32 v129, v129, 0x3c000000, v195
	v_mul_f32_e32 v130, 0x4b800000, v129
	v_cmp_gt_f32_e32 vcc, s80, v129
	s_nop 1
	v_cndmask_b32_e32 v129, v129, v130, vcc
	v_rsq_f32_e32 v129, v129
	s_nop 0
	v_mul_f32_e32 v128, 0x45800000, v129
	v_cndmask_b32_e32 v128, v129, v128, vcc
	v_mul_f32_e32 v128, v144, v128
	v_pk_mul_f32 v[132:133], v[44:45], v[128:129] op_sel_hi:[1,0]
	v_pk_mul_f32 v[130:131], v[46:47], v[128:129] op_sel_hi:[1,0]
	v_pk_mul_f32 v[186:187], v[40:41], v[128:129] op_sel_hi:[1,0]
	v_pk_mul_f32 v[134:135], v[42:43], v[128:129] op_sel_hi:[1,0]
	v_pk_mul_f32 v[130:131], v[178:179], v[130:131]
	v_pk_mul_f32 v[128:129], v[180:181], v[132:133]
	v_pk_mul_f32 v[134:135], v[174:175], v[134:135]
	v_pk_mul_f32 v[132:133], v[176:177], v[186:187]
	s_and_b64 vcc, exec, s[18:19]
	s_cbranch_vccnz .LBB0_1163
	v_mad_i64_i32 v[198:199], s[0:1], v192, s36, v[172:173]
	v_add_co_u32_e32 v198, vcc, 0x15c2f000, v198
	v_cvt_pk_bf16_f32 v186, v128, v129
	v_cvt_pk_bf16_f32 v187, v130, v131
	v_addc_co_u32_e32 v199, vcc, 0, v199, vcc
	global_store_dwordx2 v[198:199], v[186:187], off
	v_cvt_pk_bf16_f32 v186, v132, v133
	v_cvt_pk_bf16_f32 v187, v134, v135
	s_mov_b64 s[0:1], 0
	global_store_dwordx2 v[198:199], v[186:187], off offset:32

.LBB0_1167:
	v_add_u32_e32 v128, 0xb0, v137
	v_lshlrev_b32_e32 v137, 3, v128
	v_mov_b32_e32 v129, v231
	v_add_u32_e32 v186, s50, v128
	s_mov_b64 s[0:1], -1
	v_mul_f32_e32 v129, v138, v129
	v_mul_f32_e32 v129, v138, v129
	v_fmamk_f32 v129, v129, 0x3c000000, v195
	v_mul_f32_e32 v130, 0x4b800000, v129
	v_cmp_gt_f32_e32 vcc, s80, v129
	s_nop 1
	v_cndmask_b32_e32 v129, v129, v130, vcc
	v_rsq_f32_e32 v129, v129
	s_nop 0
	v_mul_f32_e32 v128, 0x45800000, v129
	v_cndmask_b32_e32 v128, v129, v128, vcc
	v_mul_f32_e32 v128, v138, v128
	v_pk_mul_f32 v[132:133], v[36:37], v[128:129] op_sel_hi:[1,0]
	v_pk_mul_f32 v[130:131], v[38:39], v[128:129] op_sel_hi:[1,0]
	v_pk_mul_f32 v[198:199], v[32:33], v[128:129] op_sel_hi:[1,0]
	v_pk_mul_f32 v[134:135], v[34:35], v[128:129] op_sel_hi:[1,0]
	v_pk_mul_f32 v[130:131], v[178:179], v[130:131]
	v_pk_mul_f32 v[128:129], v[180:181], v[132:133]
	v_pk_mul_f32 v[134:135], v[174:175], v[134:135]
	v_pk_mul_f32 v[132:133], v[176:177], v[198:199]
	s_and_b64 vcc, exec, s[18:19]
	s_cbranch_vccnz .LBB0_1169
	v_mad_i64_i32 v[200:201], s[0:1], v186, s36, v[172:173]
	v_add_co_u32_e32 v200, vcc, 0x15c2f000, v200
	v_cvt_pk_bf16_f32 v198, v128, v129
	v_cvt_pk_bf16_f32 v199, v130, v131
	v_addc_co_u32_e32 v201, vcc, 0, v201, vcc
	global_store_dwordx2 v[200:201], v[198:199], off
	v_cvt_pk_bf16_f32 v198, v132, v133
	v_cvt_pk_bf16_f32 v199, v134, v135
	s_mov_b64 s[0:1], 0
	global_store_dwordx2 v[200:201], v[198:199], off offset:32

.LBB0_1173:
	v_mov_b32_e32 v128, v232
	s_mov_b64 s[0:1], -1
	v_mul_f32_e32 v128, v152, v128
	v_mul_f32_e32 v128, v152, v128
	v_fmamk_f32 v128, v128, 0x3c000000, v195
	v_mul_f32_e32 v129, 0x4b800000, v128
	v_cmp_gt_f32_e32 vcc, s80, v128
	s_nop 1
	v_cndmask_b32_e32 v128, v128, v129, vcc
	v_rsq_f32_e32 v128, v128
	s_nop 0
	v_mul_f32_e32 v129, 0x45800000, v128
	v_cndmask_b32_e32 v128, v128, v129, vcc
	v_mul_f32_e32 v128, v152, v128
	v_pk_mul_f32 v[132:133], v[28:29], v[128:129] op_sel_hi:[1,0]
	v_pk_mul_f32 v[130:131], v[30:31], v[128:129] op_sel_hi:[1,0]
	v_pk_mul_f32 v[184:185], v[24:25], v[128:129] op_sel_hi:[1,0]
	v_pk_mul_f32 v[134:135], v[26:27], v[128:129] op_sel_hi:[1,0]
	v_pk_mul_f32 v[130:131], v[178:179], v[130:131]
	v_pk_mul_f32 v[128:129], v[180:181], v[132:133]
	v_pk_mul_f32 v[134:135], v[174:175], v[134:135]
	v_pk_mul_f32 v[132:133], v[176:177], v[184:185]
	s_and_b64 vcc, exec, s[18:19]
	s_cbranch_vccnz .LBB0_1175
	v_mad_i64_i32 v[198:199], s[0:1], v188, s36, v[172:173]
	v_add_co_u32_e32 v198, vcc, 0x15c2f000, v198
	v_cvt_pk_bf16_f32 v184, v128, v129
	v_cvt_pk_bf16_f32 v185, v130, v131
	v_addc_co_u32_e32 v199, vcc, 0, v199, vcc
	global_store_dwordx2 v[198:199], v[184:185], off offset:256
	v_cvt_pk_bf16_f32 v184, v132, v133
	v_cvt_pk_bf16_f32 v185, v134, v135
	s_mov_b64 s[0:1], 0
	global_store_dwordx2 v[198:199], v[184:185], off offset:288

.LBB0_1179:
	v_mov_b32_e32 v128, v233
	s_mov_b64 s[0:1], -1
	v_mul_f32_e32 v128, v148, v128
	v_mul_f32_e32 v128, v148, v128
	v_fmamk_f32 v128, v128, 0x3c000000, v195
	v_mul_f32_e32 v129, 0x4b800000, v128
	v_cmp_gt_f32_e32 vcc, s80, v128
	s_nop 1
	v_cndmask_b32_e32 v128, v128, v129, vcc
	v_rsq_f32_e32 v128, v128
	s_nop 0
	v_mul_f32_e32 v129, 0x45800000, v128
	v_cndmask_b32_e32 v128, v128, v129, vcc
	v_mul_f32_e32 v128, v148, v128
	v_pk_mul_f32 v[132:133], v[20:21], v[128:129] op_sel_hi:[1,0]
	v_pk_mul_f32 v[130:131], v[22:23], v[128:129] op_sel_hi:[1,0]
	v_pk_mul_f32 v[184:185], v[16:17], v[128:129] op_sel_hi:[1,0]
	v_pk_mul_f32 v[134:135], v[18:19], v[128:129] op_sel_hi:[1,0]
	v_pk_mul_f32 v[130:131], v[178:179], v[130:131]
	v_pk_mul_f32 v[128:129], v[180:181], v[132:133]
	v_pk_mul_f32 v[134:135], v[174:175], v[134:135]
	v_pk_mul_f32 v[132:133], v[176:177], v[184:185]
	s_and_b64 vcc, exec, s[18:19]
	s_cbranch_vccnz .LBB0_1181
	v_mad_i64_i32 v[188:189], s[0:1], v190, s36, v[172:173]
	v_add_co_u32_e32 v188, vcc, 0x15c2f000, v188
	v_cvt_pk_bf16_f32 v184, v128, v129
	v_cvt_pk_bf16_f32 v185, v130, v131
	v_addc_co_u32_e32 v189, vcc, 0, v189, vcc
	global_store_dwordx2 v[188:189], v[184:185], off offset:256
	v_cvt_pk_bf16_f32 v184, v132, v133
	v_cvt_pk_bf16_f32 v185, v134, v135
	s_mov_b64 s[0:1], 0
	global_store_dwordx2 v[188:189], v[184:185], off offset:288

.LBB0_1185:
	v_mov_b32_e32 v128, v234
	s_mov_b64 s[0:1], -1
	v_mul_f32_e32 v128, v144, v128
	v_mul_f32_e32 v128, v144, v128
	v_fmamk_f32 v128, v128, 0x3c000000, v195
	v_mul_f32_e32 v129, 0x4b800000, v128
	v_cmp_gt_f32_e32 vcc, s80, v128
	s_nop 1
	v_cndmask_b32_e32 v128, v128, v129, vcc
	v_rsq_f32_e32 v128, v128
	s_nop 0
	v_mul_f32_e32 v129, 0x45800000, v128
	v_cndmask_b32_e32 v128, v128, v129, vcc
	v_mul_f32_e32 v128, v144, v128
	v_pk_mul_f32 v[132:133], v[12:13], v[128:129] op_sel_hi:[1,0]
	v_pk_mul_f32 v[130:131], v[14:15], v[128:129] op_sel_hi:[1,0]
	v_pk_mul_f32 v[184:185], v[8:9], v[128:129] op_sel_hi:[1,0]
	v_pk_mul_f32 v[134:135], v[10:11], v[128:129] op_sel_hi:[1,0]
	v_pk_mul_f32 v[130:131], v[178:179], v[130:131]
	v_pk_mul_f32 v[128:129], v[180:181], v[132:133]
	v_pk_mul_f32 v[134:135], v[174:175], v[134:135]
	v_pk_mul_f32 v[132:133], v[176:177], v[184:185]
	s_and_b64 vcc, exec, s[18:19]
	s_cbranch_vccnz .LBB0_1187
	v_mad_i64_i32 v[188:189], s[0:1], v192, s36, v[172:173]
	v_add_co_u32_e32 v188, vcc, 0x15c2f000, v188
	v_cvt_pk_bf16_f32 v184, v128, v129
	v_cvt_pk_bf16_f32 v185, v130, v131
	v_addc_co_u32_e32 v189, vcc, 0, v189, vcc
	global_store_dwordx2 v[188:189], v[184:185], off offset:256
	v_cvt_pk_bf16_f32 v184, v132, v133
	v_cvt_pk_bf16_f32 v185, v134, v135
	s_mov_b64 s[0:1], 0
	global_store_dwordx2 v[188:189], v[184:185], off offset:288

.LBB0_1191:
	v_mov_b32_e32 v128, v235
	s_mov_b64 s[0:1], -1
	v_mul_f32_e32 v128, v138, v128
	v_mul_f32_e32 v128, v138, v128
	v_fmamk_f32 v128, v128, 0x3c000000, v195
	v_cmp_gt_f32_e32 vcc, s80, v128
	v_mul_f32_e32 v129, 0x4b800000, v128
	s_nop 0
	v_cndmask_b32_e32 v128, v128, v129, vcc
	v_rsq_f32_e32 v128, v128
	s_nop 0
	v_mul_f32_e32 v129, 0x45800000, v128
	v_cndmask_b32_e32 v128, v128, v129, vcc
	v_mul_f32_e32 v132, v138, v128
	v_pk_mul_f32 v[130:131], v[6:7], v[132:133] op_sel_hi:[1,0]
	v_pk_mul_f32 v[128:129], v[4:5], v[132:133] op_sel_hi:[1,0]
	v_pk_mul_f32 v[130:131], v[178:179], v[130:131]
	v_pk_mul_f32 v[178:179], v[0:1], v[132:133] op_sel_hi:[1,0]
	v_pk_mul_f32 v[132:133], v[2:3], v[132:133] op_sel_hi:[1,0]
	v_pk_mul_f32 v[128:129], v[180:181], v[128:129]
	v_pk_mul_f32 v[134:135], v[174:175], v[132:133]
	v_pk_mul_f32 v[132:133], v[176:177], v[178:179]
	s_and_b64 vcc, exec, s[18:19]
	s_cbranch_vccnz .LBB0_1193
	v_mad_i64_i32 v[172:173], s[0:1], v186, s36, v[172:173]
	v_add_co_u32_e32 v172, vcc, 0x15c2f000, v172
	v_cvt_pk_bf16_f32 v174, v128, v129
	v_cvt_pk_bf16_f32 v175, v130, v131
	v_addc_co_u32_e32 v173, vcc, 0, v173, vcc
	global_store_dwordx2 v[172:173], v[174:175], off offset:256
	v_cvt_pk_bf16_f32 v174, v132, v133
	v_cvt_pk_bf16_f32 v175, v134, v135
	s_mov_b64 s[0:1], 0
	global_store_dwordx2 v[172:173], v[174:175], off offset:288
